# K-loop heads aligned to 64-byte instruction-cache lines (.p2align 6, s_nop fill)
# baseline (speedup 1.0000x reference)
.Lprio_skip0:
	.p2align 6
